# lora-input pass processes two tokens per iteration with both tokens' loads in flight
# baseline (speedup 1.0000x reference)
; __device__ __forceinline__ float sigmoidf_(float z) { return __builtin_amdgcn_rcpf(1.0f + __expf(-z)); }
; __device__ __forceinline__ void seq_pos(int t, int& pos, int& len) { if (t < TP) { pos = t & 2047; len = 2048; } else { pos = (t - TP) & 4095; len = 4096; } }
; __device__ __forceinline__ void ld8(const bf16_t* p, float (&o)[8]) { const u32x4 w = *(const u32x4*)p; o[0] = bflo(w.x); o[1] = bfhi(w.x); o[2] = bflo(w.y); o[3] = bfhi(w.y); o[4] = bflo(w.z); o[5] = bfhi(w.z); o[6] = bflo(w.w); o[7] = bfhi(w.w); }
; __device__ __forceinline__ void shift8(const bf16_t* P, int col, bool first, bool last, const float (&mp)[8], const float (&mn)[8], float (&o)[8]) {
;     float c[8], pv[8], nx[8];
;     ld8(P + col, c); ld8(P + col - (first ? 0 : PROJ_LD), pv); ld8(P + col + (last ? 0 : PROJ_LD), nx);
; #pragma unroll
;     for (int j = 0; j < 8; ++j) { const float pp = first ? 0.f : pv[j], pn = last ? 0.f : nx[j]; o[j] = c[j] + mp[j] * (pp - c[j]) + mn[j] * (pn - c[j]); }
; }
; __device__ __forceinline__ void p2_phase(KA a, int G, const int tid, const int bid) {
;     ...
;     for (int t = gw; t < T_ALL; t += NGW) {
;         int pos, len; seq_pos(t, pos, len); const bool first = pos == 0, last = pos == len - 1;
;         const bf16_t* P = PROJ + (size_t)t * PROJ_LD;
;         float sh[8], kk[8];
;         shift8(P, lcol, first, last, mpl, mnl, sh);
;         shift8(P, kcol, first, last, mpk, mnk, kk);
;         if (lane < 16) {
; #pragma unroll
;             for (int j = 0; j < 8; ++j) sh[j] = 1.0f - 2.0f * __builtin_amdgcn_rcpf(__expf(2.0f * sh[j]) + 1.0f);
;         } else if (lane >= 32) {
; #pragma unroll
;             for (int j = 0; j < 8; ++j) sh[j] = sigmoidf_(sh[j]);
;         }
.LBB0_196:
	s_or_b64 exec, exec, s[8:9]
	v_lshl_add_u32 v16, s24, 1, v16
	v_cmp_lt_i32_e64 s[8:9], s81, v16
	s_or_b64 s[18:19], s[8:9], s[18:19]
	s_andn2_b64 exec, exec, s[18:19]
	s_cbranch_execz .LBB0_205
.LBB0_197:
	s_waitcnt lgkmcnt(0)
	v_mov_b64_e32 v[44:45], s[16:17]
	v_mad_i64_i32 v[44:45], s[8:9], v16, s85, v[44:45]
	v_cmp_gt_i32_e64 s[8:9], s83, v16
	v_lshl_add_u64 v[46:47], v[44:45], 0, v[18:19]
	v_mov_b32_e32 v49, v19
	v_cndmask_b32_e64 v17, v170, v171, s[8:9]
	v_and_b32_e32 v52, v17, v16
	v_cmp_eq_u32_e64 s[8:9], v52, v17
	v_cmp_eq_u32_e64 s[10:11], 0, v52
	v_mov_b32_e32 v61, v19
	v_cndmask_b32_e64 v48, v173, 0, s[8:9]
	v_lshl_add_u64 v[50:51], v[46:47], 0, v[48:49]
	global_load_dwordx4 v[78:81], v[50:51], off
	v_cndmask_b32_e64 v51, -1, 0, s[10:11]
	v_cndmask_b32_e64 v50, v172, 0, s[10:11]
	v_lshl_add_u64 v[44:45], v[44:45], 0, v[60:61]
	global_load_dwordx4 v[74:77], v[46:47], off
	global_load_dwordx4 v[52:55], v[44:45], off offset:1024
	v_lshl_add_u64 v[46:47], v[46:47], 0, v[50:51]
	global_load_dwordx4 v[82:85], v[46:47], off
	v_lshl_add_u64 v[46:47], v[44:45], 0, v[48:49]
	v_lshl_add_u64 v[44:45], v[44:45], 0, v[50:51]
	global_load_dwordx4 v[48:51], v[44:45], off offset:1024
	s_nop 0
	global_load_dwordx4 v[44:47], v[46:47], off offset:1024
	v_add_u32_e32 v126, s24, v16
	v_cmp_ge_i32_e64 s[50:51], s81, v126
	s_nop 1
	v_cndmask_b32_e64 v126, v16, v126, s[50:51]
	s_waitcnt lgkmcnt(0)
	v_mov_b64_e32 v[88:89], s[16:17]
	v_mad_i64_i32 v[88:89], s[42:43], v126, s85, v[88:89]
	v_cmp_gt_i32_e64 s[42:43], s83, v126
	v_lshl_add_u64 v[90:91], v[88:89], 0, v[18:19]
	v_mov_b32_e32 v93, v19
	v_cndmask_b32_e64 v127, v170, v171, s[42:43]
	v_and_b32_e32 v96, v127, v126
	v_cmp_eq_u32_e64 s[42:43], v96, v127
	v_cmp_eq_u32_e64 s[44:45], 0, v96
	v_mov_b32_e32 v61, v19
	v_cndmask_b32_e64 v92, v173, 0, s[42:43]
	v_lshl_add_u64 v[94:95], v[90:91], 0, v[92:93]
	global_load_dwordx4 v[116:119], v[94:95], off
	v_cndmask_b32_e64 v95, -1, 0, s[44:45]
	v_cndmask_b32_e64 v94, v172, 0, s[44:45]
	v_lshl_add_u64 v[88:89], v[88:89], 0, v[60:61]
	global_load_dwordx4 v[112:115], v[90:91], off
	global_load_dwordx4 v[96:99], v[88:89], off offset:1024
	v_lshl_add_u64 v[90:91], v[90:91], 0, v[94:95]
	global_load_dwordx4 v[120:123], v[90:91], off
	v_lshl_add_u64 v[90:91], v[88:89], 0, v[92:93]
	v_lshl_add_u64 v[88:89], v[88:89], 0, v[94:95]
	global_load_dwordx4 v[92:95], v[88:89], off offset:1024
	s_nop 0
	global_load_dwordx4 v[88:91], v[90:91], off offset:1024
	s_waitcnt vmcnt(11)
	v_lshlrev_b32_e32 v73, 16, v79
	v_lshlrev_b32_e32 v17, 16, v78
	v_and_b32_e32 v61, 0xffff0000, v78
	v_cndmask_b32_e64 v17, v17, 0, s[8:9]
	s_waitcnt vmcnt(10)
	v_lshlrev_b32_e32 v66, 16, v74
	v_and_b32_e32 v67, 0xffff0000, v74
	v_and_b32_e32 v74, 0xffff0000, v79
	s_waitcnt vmcnt(8)
	v_lshlrev_b32_e32 v79, 16, v82
	v_lshlrev_b32_e32 v64, 16, v75
	v_and_b32_e32 v65, 0xffff0000, v75
	v_lshlrev_b32_e32 v62, 16, v76
	v_and_b32_e32 v63, 0xffff0000, v76
	v_lshlrev_b32_e32 v75, 16, v80
	v_and_b32_e32 v76, 0xffff0000, v80
	v_and_b32_e32 v80, 0xffff0000, v82
	v_cndmask_b32_e64 v79, v79, 0, s[10:11]
	v_cndmask_b32_e64 v80, v80, 0, s[10:11]
	v_sub_f32_e32 v79, v79, v66
	v_lshlrev_b32_e32 v68, 16, v77
	v_and_b32_e32 v69, 0xffff0000, v77
	v_lshlrev_b32_e32 v77, 16, v81
	v_and_b32_e32 v78, 0xffff0000, v81
	v_lshlrev_b32_e32 v81, 16, v83
	v_and_b32_e32 v82, 0xffff0000, v83
	v_lshlrev_b32_e32 v83, 16, v84
	v_and_b32_e32 v84, 0xffff0000, v84
	v_lshlrev_b32_e32 v86, 16, v85
	v_and_b32_e32 v85, 0xffff0000, v85
	v_cndmask_b32_e64 v61, v61, 0, s[8:9]
	v_sub_f32_e32 v17, v17, v66
	v_sub_f32_e32 v80, v80, v67
	v_fmac_f32_e32 v66, v0, v79
	v_sub_f32_e32 v61, v61, v67
	v_cndmask_b32_e64 v81, v81, 0, s[10:11]
	v_cndmask_b32_e64 v82, v82, 0, s[10:11]
	v_cndmask_b32_e64 v83, v83, 0, s[10:11]
	v_cndmask_b32_e64 v84, v84, 0, s[10:11]
	v_cndmask_b32_e64 v86, v86, 0, s[10:11]
	v_fmac_f32_e32 v67, v1, v80
	v_fmac_f32_e32 v66, v4, v17
	v_cndmask_b32_e64 v17, v85, 0, s[10:11]
	v_cndmask_b32_e64 v73, v73, 0, s[8:9]
	v_cndmask_b32_e64 v74, v74, 0, s[8:9]
	v_cndmask_b32_e64 v75, v75, 0, s[8:9]
	v_cndmask_b32_e64 v76, v76, 0, s[8:9]
	v_cndmask_b32_e64 v77, v77, 0, s[8:9]
	v_sub_f32_e32 v81, v81, v64
	v_sub_f32_e32 v82, v82, v65
	v_sub_f32_e32 v83, v83, v62
	v_sub_f32_e32 v84, v84, v63
	v_sub_f32_e32 v86, v86, v68
	v_fmac_f32_e32 v67, v5, v61
	v_cndmask_b32_e64 v61, v78, 0, s[8:9]
	v_sub_f32_e32 v17, v17, v69
	v_sub_f32_e32 v73, v73, v64
	v_sub_f32_e32 v74, v74, v65
	v_sub_f32_e32 v75, v75, v62
	v_sub_f32_e32 v76, v76, v63
	v_sub_f32_e32 v77, v77, v68
	v_fmac_f32_e32 v64, v2, v81
	v_fmac_f32_e32 v65, v3, v82
	v_fmac_f32_e32 v62, v8, v83
	v_fmac_f32_e32 v63, v9, v84
	v_fmac_f32_e32 v68, v10, v86
	v_sub_f32_e32 v61, v61, v69
	v_fmac_f32_e32 v69, v11, v17
	v_fmac_f32_e32 v64, v6, v73
	v_fmac_f32_e32 v65, v7, v74
	v_fmac_f32_e32 v62, v12, v75
	v_fmac_f32_e32 v63, v13, v76
	v_fmac_f32_e32 v68, v14, v77
	v_fmac_f32_e32 v69, v15, v61
	s_and_saveexec_b64 s[20:21], vcc
	s_xor_b64 s[20:21], exec, s[20:21]
	s_cbranch_execz .LBB0_201
	s_and_saveexec_b64 s[22:23], s[2:3]
	s_cbranch_execz .LBB0_200
	v_mul_f32_e32 v17, 0xbfb8aa3b, v66
	v_exp_f32_e32 v17, v17
	v_mul_f32_e32 v61, 0xbfb8aa3b, v67
	v_exp_f32_e32 v61, v61
	v_add_f32_e32 v17, 1.0, v17
	v_rcp_f32_e32 v66, v17
	v_mul_f32_e32 v17, 0xbfb8aa3b, v64
	v_add_f32_e32 v61, 1.0, v61
	v_exp_f32_e32 v17, v17
	v_mul_f32_e32 v64, 0xbfb8aa3b, v65
	v_exp_f32_e32 v65, v64
	v_rcp_f32_e32 v67, v61
	v_mul_f32_e32 v61, 0xbfb8aa3b, v62
	v_exp_f32_e32 v61, v61
	v_mul_f32_e32 v62, 0xbfb8aa3b, v63
	v_exp_f32_e32 v63, v62
	v_add_f32_e32 v17, 1.0, v17
	v_rcp_f32_e32 v64, v17
	v_add_f32_e32 v17, 1.0, v65
	v_rcp_f32_e32 v65, v17
	v_add_f32_e32 v17, 1.0, v61
	v_mul_f32_e32 v61, 0xbfb8aa3b, v68
	v_rcp_f32_e32 v62, v17
	v_add_f32_e32 v17, 1.0, v63
	v_exp_f32_e32 v61, v61
	v_mul_f32_e32 v63, 0xbfb8aa3b, v69
	v_exp_f32_e32 v69, v63
	v_rcp_f32_e32 v63, v17
	v_add_f32_e32 v17, 1.0, v61
	v_rcp_f32_e32 v68, v17
	v_add_f32_e32 v17, 1.0, v69
	v_rcp_f32_e32 v69, v17

; __device__ __forceinline__ float sigmoidf_(float z) { return __builtin_amdgcn_rcpf(1.0f + __expf(-z)); }
; __device__ __forceinline__ void seq_pos(int t, int& pos, int& len) { if (t < TP) { pos = t & 2047; len = 2048; } else { pos = (t - TP) & 4095; len = 4096; } }
; __device__ __forceinline__ u32x4 st8(const float (&v)[8]) { u32x4 w; w.x = pk2(v[0], v[1]); w.y = pk2(v[2], v[3]); w.z = pk2(v[4], v[5]); w.w = pk2(v[6], v[7]); return w; }
; __device__ __forceinline__ void p2_phase(KA a, int G, const int tid, const int bid) {
;     ...
;     for (int t = gw; t < T_ALL; t += NGW) {
;         int pos, len; seq_pos(t, pos, len); const bool first = pos == 0, last = pos == len - 1;
;         const bf16_t* P = PROJ + (size_t)t * PROJ_LD;
;         float sh[8], kk[8];
;         shift8(P, lcol, first, last, mpl, mnl, sh);
;         shift8(P, kcol, first, last, mpk, mnk, kk);
;         if (lane < 16) {
; #pragma unroll
;             for (int j = 0; j < 8; ++j) sh[j] = 1.0f - 2.0f * __builtin_amdgcn_rcpf(__expf(2.0f * sh[j]) + 1.0f);
;         } else if (lane >= 32) {
; #pragma unroll
;             for (int j = 0; j < 8; ++j) sh[j] = sigmoidf_(sh[j]);
;         }
;         if (lane >= 52) {
; #pragma unroll
;             for (int j = 0; j < 8; ++j) sh[j] = 0.f;
;         }
;         *(u32x4*)(AL + (size_t)t * 512 + 8 * lane) = st8(sh);
;         float s = 0.f;
; #pragma unroll
;         for (int j = 0; j < 8; ++j) { const float x = kk[j] * kkv[j]; s += x * x; }
;         s += __shfl_xor(s, 1); s += __shfl_xor(s, 2); s += __shfl_xor(s, 4);
;         if ((lane & 7) == 0) KSC[(size_t)t * 8 + (lane >> 3)] = __builtin_amdgcn_rsqf(s + 1e-12f);
;     }
.LBB0_203:
	s_or_b64 exec, exec, s[20:21]
	s_waitcnt vmcnt(7)
	v_lshlrev_b32_e32 v76, 16, v48
	v_and_b32_e32 v48, 0xffff0000, v48
	v_lshlrev_b32_e32 v61, 16, v52
	v_and_b32_e32 v52, 0xffff0000, v52
	s_waitcnt vmcnt(6)
	v_lshlrev_b32_e32 v80, 16, v44
	v_and_b32_e32 v44, 0xffff0000, v44
	v_cndmask_b32_e64 v48, v48, 0, s[10:11]
	v_cndmask_b32_e64 v44, v44, 0, s[8:9]
	v_sub_f32_e32 v48, v48, v52
	v_lshlrev_b32_e32 v77, 16, v49
	v_sub_f32_e32 v44, v44, v52
	v_fmac_f32_e32 v52, v21, v48
	v_lshlrev_b32_e32 v73, 16, v53
	v_lshlrev_b32_e32 v81, 16, v45
	v_fmac_f32_e32 v52, v25, v44
	v_cndmask_b32_e64 v44, v77, 0, s[10:11]
	v_and_b32_e32 v49, 0xffff0000, v49
	v_cndmask_b32_e64 v48, v81, 0, s[8:9]
	v_sub_f32_e32 v44, v44, v73
	v_and_b32_e32 v53, 0xffff0000, v53
	v_and_b32_e32 v45, 0xffff0000, v45
	v_sub_f32_e32 v48, v48, v73
	v_fmac_f32_e32 v73, v22, v44
	v_cndmask_b32_e64 v44, v49, 0, s[10:11]
	v_lshlrev_b32_e32 v78, 16, v50
	v_cndmask_b32_e64 v45, v45, 0, s[8:9]
	v_sub_f32_e32 v44, v44, v53
	v_lshlrev_b32_e32 v74, 16, v54
	v_lshlrev_b32_e32 v82, 16, v46
	v_sub_f32_e32 v45, v45, v53
	v_fmac_f32_e32 v53, v23, v44
	v_cndmask_b32_e64 v44, v78, 0, s[10:11]
	v_and_b32_e32 v50, 0xffff0000, v50
	v_fmac_f32_e32 v53, v27, v45
	v_cndmask_b32_e64 v45, v82, 0, s[8:9]
	v_sub_f32_e32 v44, v44, v74
	v_and_b32_e32 v54, 0xffff0000, v54
	v_and_b32_e32 v46, 0xffff0000, v46
	v_sub_f32_e32 v45, v45, v74
	v_fmac_f32_e32 v74, v28, v44
	v_cndmask_b32_e64 v44, v50, 0, s[10:11]
	v_lshlrev_b32_e32 v79, 16, v51
	v_fmac_f32_e32 v74, v32, v45
	v_cndmask_b32_e64 v45, v46, 0, s[8:9]
	v_sub_f32_e32 v44, v44, v54
	v_lshlrev_b32_e32 v75, 16, v55
	v_lshlrev_b32_e32 v83, 16, v47
	v_sub_f32_e32 v45, v45, v54
	v_fmac_f32_e32 v54, v29, v44
	v_cndmask_b32_e64 v44, v79, 0, s[10:11]
	v_and_b32_e32 v51, 0xffff0000, v51
	v_cndmask_b32_e64 v76, v76, 0, s[10:11]
	v_fmac_f32_e32 v54, v33, v45
	v_cndmask_b32_e64 v45, v83, 0, s[8:9]
	v_sub_f32_e32 v44, v44, v75
	v_and_b32_e32 v55, 0xffff0000, v55
	v_and_b32_e32 v47, 0xffff0000, v47
	v_cndmask_b32_e64 v80, v80, 0, s[8:9]
	v_sub_f32_e32 v76, v76, v61
	v_sub_f32_e32 v45, v45, v75
	v_fmac_f32_e32 v75, v30, v44
	v_cndmask_b32_e64 v44, v51, 0, s[10:11]
	v_sub_f32_e32 v80, v80, v61
	v_fmac_f32_e32 v61, v20, v76
	v_fmac_f32_e32 v75, v34, v45
	v_cndmask_b32_e64 v45, v47, 0, s[8:9]
	v_sub_f32_e32 v44, v44, v55
	v_fmac_f32_e32 v61, v24, v80
	v_sub_f32_e32 v45, v45, v55
	v_fmac_f32_e32 v55, v31, v44
	v_mul_f32_e32 v46, v37, v52
	v_fmac_f32_e32 v73, v26, v48
	v_fmac_f32_e32 v55, v35, v45
	v_mul_f32_e32 v45, v36, v61
	v_mul_f32_e32 v46, v46, v46
	v_fmac_f32_e32 v46, v45, v45
	v_mul_f32_e32 v45, v38, v73
	v_fmac_f32_e32 v46, v45, v45
	v_mul_f32_e32 v45, v39, v53
	v_fmac_f32_e32 v46, v45, v45
	v_mul_f32_e32 v45, v40, v74
	v_fmac_f32_e32 v46, v45, v45
	v_mul_f32_e32 v45, v41, v54
	v_fmac_f32_e32 v46, v45, v45
	v_mul_f32_e32 v45, v42, v75
	v_fmac_f32_e32 v46, v45, v45
	v_mul_f32_e32 v45, v43, v55
	v_fmac_f32_e32 v46, v45, v45
	ds_bpermute_b32 v45, v70, v46
	v_cndmask_b32_e64 v44, v63, 0, s[4:5]
	v_cndmask_b32_e64 v48, v62, 0, s[4:5]
	v_cvt_pk_bf16_f32 v48, v48, v44
	v_ashrrev_i32_e32 v17, 31, v16
	s_waitcnt lgkmcnt(0)
	v_add_f32_e32 v45, v46, v45
	ds_bpermute_b32 v53, v71, v45
	v_cndmask_b32_e64 v49, v69, 0, s[4:5]
	v_cndmask_b32_e64 v50, v68, 0, s[4:5]
	v_cndmask_b32_e64 v47, v65, 0, s[4:5]
	v_cndmask_b32_e64 v51, v64, 0, s[4:5]
	s_waitcnt lgkmcnt(0)
	v_add_f32_e32 v44, v45, v53
	ds_bpermute_b32 v45, v72, v44
	v_cndmask_b32_e64 v52, v67, 0, s[4:5]
	v_cndmask_b32_e64 v46, v66, 0, s[4:5]
	v_cvt_pk_bf16_f32 v47, v51, v47
	v_cvt_pk_bf16_f32 v49, v50, v49
	v_lshlrev_b64 v[50:51], 10, v[16:17]
	v_cvt_pk_bf16_f32 v46, v46, v52
	v_lshl_add_u64 v[50:51], v[56:57], 0, v[50:51]
	global_store_dwordx4 v[50:51], v[46:49], off
	s_and_saveexec_b64 s[8:9], s[6:7]
	s_cbranch_execz .Lp2_mid
	s_waitcnt lgkmcnt(0)
	v_add_f32_e32 v44, v44, v45
	v_add_f32_e32 v44, 0x2b8cbccc, v44
	v_rsq_f32_e32 v46, v44
	v_lshlrev_b64 v[44:45], 5, v[16:17]
	v_lshl_add_u64 v[44:45], v[58:59], 0, v[44:45]
	global_store_dword v[44:45], v46, off
	s_branch .Lp2_mid
.Lp2_mid:
	s_or_b64 exec, exec, s[8:9]
	s_and_b64 s[52:53], exec, s[50:51]
	s_cbranch_scc0 .LBB0_196
	s_waitcnt vmcnt(7)
	v_lshlrev_b32_e32 v111, 16, v117
	v_lshlrev_b32_e32 v127, 16, v116
	v_and_b32_e32 v101, 0xffff0000, v116
	v_cndmask_b32_e64 v127, v127, 0, s[42:43]
	s_waitcnt vmcnt(6)
	v_lshlrev_b32_e32 v106, 16, v112
	v_and_b32_e32 v107, 0xffff0000, v112
	v_and_b32_e32 v112, 0xffff0000, v117
	s_waitcnt vmcnt(4)
	v_lshlrev_b32_e32 v117, 16, v120
	v_lshlrev_b32_e32 v104, 16, v113
	v_and_b32_e32 v105, 0xffff0000, v113
	v_lshlrev_b32_e32 v102, 16, v114
	v_and_b32_e32 v103, 0xffff0000, v114
	v_lshlrev_b32_e32 v113, 16, v118
	v_and_b32_e32 v114, 0xffff0000, v118
	v_and_b32_e32 v118, 0xffff0000, v120
	v_cndmask_b32_e64 v117, v117, 0, s[44:45]
	v_cndmask_b32_e64 v118, v118, 0, s[44:45]
	v_sub_f32_e32 v117, v117, v106
	v_lshlrev_b32_e32 v108, 16, v115
	v_and_b32_e32 v109, 0xffff0000, v115
	v_lshlrev_b32_e32 v115, 16, v119
	v_and_b32_e32 v116, 0xffff0000, v119
	v_lshlrev_b32_e32 v119, 16, v121
	v_and_b32_e32 v120, 0xffff0000, v121
	v_lshlrev_b32_e32 v121, 16, v122
	v_and_b32_e32 v122, 0xffff0000, v122
	v_lshlrev_b32_e32 v124, 16, v123
	v_and_b32_e32 v123, 0xffff0000, v123
	v_cndmask_b32_e64 v101, v101, 0, s[42:43]
	v_sub_f32_e32 v127, v127, v106
	v_sub_f32_e32 v118, v118, v107
	v_fmac_f32_e32 v106, v0, v117
	v_sub_f32_e32 v101, v101, v107
	v_cndmask_b32_e64 v119, v119, 0, s[44:45]
	v_cndmask_b32_e64 v120, v120, 0, s[44:45]
	v_cndmask_b32_e64 v121, v121, 0, s[44:45]
	v_cndmask_b32_e64 v122, v122, 0, s[44:45]
	v_cndmask_b32_e64 v124, v124, 0, s[44:45]
	v_fmac_f32_e32 v107, v1, v118
	v_fmac_f32_e32 v106, v4, v127
	v_cndmask_b32_e64 v127, v123, 0, s[44:45]
	v_cndmask_b32_e64 v111, v111, 0, s[42:43]
	v_cndmask_b32_e64 v112, v112, 0, s[42:43]
	v_cndmask_b32_e64 v113, v113, 0, s[42:43]
	v_cndmask_b32_e64 v114, v114, 0, s[42:43]
	v_cndmask_b32_e64 v115, v115, 0, s[42:43]
	v_sub_f32_e32 v119, v119, v104
	v_sub_f32_e32 v120, v120, v105
	v_sub_f32_e32 v121, v121, v102
	v_sub_f32_e32 v122, v122, v103
	v_sub_f32_e32 v124, v124, v108
	v_fmac_f32_e32 v107, v5, v101
	v_cndmask_b32_e64 v101, v116, 0, s[42:43]
	v_sub_f32_e32 v127, v127, v109
	v_sub_f32_e32 v111, v111, v104
	v_sub_f32_e32 v112, v112, v105
	v_sub_f32_e32 v113, v113, v102
	v_sub_f32_e32 v114, v114, v103
	v_sub_f32_e32 v115, v115, v108
	v_fmac_f32_e32 v104, v2, v119
	v_fmac_f32_e32 v105, v3, v120
	v_fmac_f32_e32 v102, v8, v121
	v_fmac_f32_e32 v103, v9, v122
	v_fmac_f32_e32 v108, v10, v124
	v_sub_f32_e32 v101, v101, v109
	v_fmac_f32_e32 v109, v11, v127
	v_fmac_f32_e32 v104, v6, v111
	v_fmac_f32_e32 v105, v7, v112
	v_fmac_f32_e32 v102, v12, v113
	v_fmac_f32_e32 v103, v13, v114
	v_fmac_f32_e32 v108, v14, v115
	v_fmac_f32_e32 v109, v15, v101
	s_and_saveexec_b64 s[46:47], vcc
	s_xor_b64 s[46:47], exec, s[46:47]
	s_cbranch_execz .Lp2_b201
; __device__ __forceinline__ float sigmoidf_(float z) { return __builtin_amdgcn_rcpf(1.0f + __expf(-z)); }
; __device__ __forceinline__ u32x4 st8(const float (&v)[8]) { u32x4 w; w.x = pk2(v[0], v[1]); w.y = pk2(v[2], v[3]); w.z = pk2(v[4], v[5]); w.w = pk2(v[6], v[7]); return w; }
; __device__ __forceinline__ void p2_phase(KA a, int G, const int tid, const int bid) {
;     ...
;         if (lane < 16) {
; #pragma unroll
;             for (int j = 0; j < 8; ++j) sh[j] = 1.0f - 2.0f * __builtin_amdgcn_rcpf(__expf(2.0f * sh[j]) + 1.0f);
;         } else if (lane >= 32) {
; #pragma unroll
;             for (int j = 0; j < 8; ++j) sh[j] = sigmoidf_(sh[j]);
;         }
;         if (lane >= 52) {
; #pragma unroll
;             for (int j = 0; j < 8; ++j) sh[j] = 0.f;
;         }
;         *(u32x4*)(AL + (size_t)t * 512 + 8 * lane) = st8(sh);
;         float s = 0.f;
; #pragma unroll
;         for (int j = 0; j < 8; ++j) { const float x = kk[j] * kkv[j]; s += x * x; }
;         s += __shfl_xor(s, 1); s += __shfl_xor(s, 2); s += __shfl_xor(s, 4);
;         if ((lane & 7) == 0) KSC[(size_t)t * 8 + (lane >> 3)] = __builtin_amdgcn_rsqf(s + 1e-12f);
	s_and_saveexec_b64 s[48:49], s[2:3]
	s_cbranch_execz .Lp2_b200
	v_mul_f32_e32 v127, 0xbfb8aa3b, v106
	v_exp_f32_e32 v127, v127
	v_mul_f32_e32 v101, 0xbfb8aa3b, v107
	v_exp_f32_e32 v101, v101
	v_add_f32_e32 v127, 1.0, v127
	v_rcp_f32_e32 v106, v127
	v_mul_f32_e32 v127, 0xbfb8aa3b, v104
	v_add_f32_e32 v101, 1.0, v101
	v_exp_f32_e32 v127, v127
	v_mul_f32_e32 v104, 0xbfb8aa3b, v105
	v_exp_f32_e32 v105, v104
	v_rcp_f32_e32 v107, v101
	v_mul_f32_e32 v101, 0xbfb8aa3b, v102
	v_exp_f32_e32 v101, v101
	v_mul_f32_e32 v102, 0xbfb8aa3b, v103
	v_exp_f32_e32 v103, v102
	v_add_f32_e32 v127, 1.0, v127
	v_rcp_f32_e32 v104, v127
	v_add_f32_e32 v127, 1.0, v105
	v_rcp_f32_e32 v105, v127
	v_add_f32_e32 v127, 1.0, v101
	v_mul_f32_e32 v101, 0xbfb8aa3b, v108
	v_rcp_f32_e32 v102, v127
	v_add_f32_e32 v127, 1.0, v103
	v_exp_f32_e32 v101, v101
	v_mul_f32_e32 v103, 0xbfb8aa3b, v109
	v_exp_f32_e32 v109, v103
	v_rcp_f32_e32 v103, v127
	v_add_f32_e32 v127, 1.0, v101
	v_rcp_f32_e32 v108, v127
	v_add_f32_e32 v127, 1.0, v109
	v_rcp_f32_e32 v109, v127
.Lp2_b200:
	s_or_b64 exec, exec, s[48:49]
.Lp2_b201:
	s_andn2_saveexec_b64 s[46:47], s[46:47]
	s_cbranch_execz .Lp2_b203
	v_add_f32_e32 v127, v106, v106
	v_mul_f32_e32 v127, 0x3fb8aa3b, v127
	v_add_f32_e32 v101, v107, v107
	v_exp_f32_e32 v127, v127
	v_mul_f32_e32 v101, 0x3fb8aa3b, v101
	v_exp_f32_e32 v101, v101
	v_add_f32_e32 v102, v102, v102
	v_add_f32_e32 v127, 1.0, v127
	v_rcp_f32_e32 v106, v127
	v_add_f32_e32 v127, 1.0, v101
	v_add_f32_e32 v101, v104, v104
	v_mul_f32_e32 v101, 0x3fb8aa3b, v101
	v_add_f32_e32 v104, v105, v105
	v_exp_f32_e32 v101, v101
	v_mul_f32_e32 v104, 0x3fb8aa3b, v104
	v_exp_f32_e32 v105, v104
	v_add_f32_e32 v103, v103, v103
	v_add_f32_e32 v101, 1.0, v101
	v_rcp_f32_e32 v104, v101
	v_add_f32_e32 v101, 1.0, v105
	v_add_f32_e32 v105, v108, v108
	v_mul_f32_e32 v105, 0x3fb8aa3b, v105
	v_add_f32_e32 v107, v109, v109
	v_mul_f32_e32 v102, 0x3fb8aa3b, v102
	v_mul_f32_e32 v103, 0x3fb8aa3b, v103
	v_exp_f32_e32 v105, v105
	v_mul_f32_e32 v107, 0x3fb8aa3b, v107
	v_exp_f32_e32 v102, v102
	v_exp_f32_e32 v103, v103
	v_exp_f32_e32 v107, v107
	v_add_f32_e32 v105, 1.0, v105
	v_add_f32_e32 v102, 1.0, v102
	v_add_f32_e32 v103, 1.0, v103
	v_rcp_f32_e32 v108, v105
	v_add_f32_e32 v105, 1.0, v107
	v_rcp_f32_e32 v102, v102
	v_rcp_f32_e32 v109, v105
	v_rcp_f32_e32 v103, v103
	v_rcp_f32_e32 v105, v101
	v_rcp_f32_e32 v107, v127
	v_pk_fma_f32 v[108:109], v[108:109], -2.0, 1.0 op_sel_hi:[1,0,0]
	v_pk_fma_f32 v[102:103], v[102:103], -2.0, 1.0 op_sel_hi:[1,0,0]
	v_pk_fma_f32 v[104:105], v[104:105], -2.0, 1.0 op_sel_hi:[1,0,0]
	v_pk_fma_f32 v[106:107], v[106:107], -2.0, 1.0 op_sel_hi:[1,0,0]
.Lp2_b203:
	s_or_b64 exec, exec, s[46:47]
	s_waitcnt vmcnt(3)
	v_lshlrev_b32_e32 v114, 16, v92
	v_and_b32_e32 v92, 0xffff0000, v92
	v_lshlrev_b32_e32 v101, 16, v96
	v_and_b32_e32 v96, 0xffff0000, v96
	s_waitcnt vmcnt(2)
	v_lshlrev_b32_e32 v118, 16, v88
	v_and_b32_e32 v88, 0xffff0000, v88
	v_cndmask_b32_e64 v92, v92, 0, s[44:45]
	v_cndmask_b32_e64 v88, v88, 0, s[42:43]
	v_sub_f32_e32 v92, v92, v96
	v_lshlrev_b32_e32 v115, 16, v93
	v_sub_f32_e32 v88, v88, v96
	v_fmac_f32_e32 v96, v21, v92
	v_lshlrev_b32_e32 v111, 16, v97
	v_lshlrev_b32_e32 v119, 16, v89
	v_fmac_f32_e32 v96, v25, v88
	v_cndmask_b32_e64 v88, v115, 0, s[44:45]
	v_and_b32_e32 v93, 0xffff0000, v93
	v_cndmask_b32_e64 v92, v119, 0, s[42:43]
	v_sub_f32_e32 v88, v88, v111
	v_and_b32_e32 v97, 0xffff0000, v97
	v_and_b32_e32 v89, 0xffff0000, v89
	v_sub_f32_e32 v92, v92, v111
	v_fmac_f32_e32 v111, v22, v88
	v_cndmask_b32_e64 v88, v93, 0, s[44:45]
	v_lshlrev_b32_e32 v116, 16, v94
	v_cndmask_b32_e64 v89, v89, 0, s[42:43]
	v_sub_f32_e32 v88, v88, v97
	v_lshlrev_b32_e32 v112, 16, v98
	v_lshlrev_b32_e32 v120, 16, v90
	v_sub_f32_e32 v89, v89, v97
	v_fmac_f32_e32 v97, v23, v88
	v_cndmask_b32_e64 v88, v116, 0, s[44:45]
	v_and_b32_e32 v94, 0xffff0000, v94
	v_fmac_f32_e32 v97, v27, v89
	v_cndmask_b32_e64 v89, v120, 0, s[42:43]
	v_sub_f32_e32 v88, v88, v112
	v_and_b32_e32 v98, 0xffff0000, v98
	v_and_b32_e32 v90, 0xffff0000, v90
	v_sub_f32_e32 v89, v89, v112
	v_fmac_f32_e32 v112, v28, v88
	v_cndmask_b32_e64 v88, v94, 0, s[44:45]
	v_lshlrev_b32_e32 v117, 16, v95
	v_fmac_f32_e32 v112, v32, v89
	v_cndmask_b32_e64 v89, v90, 0, s[42:43]
	v_sub_f32_e32 v88, v88, v98
	v_lshlrev_b32_e32 v113, 16, v99
	v_lshlrev_b32_e32 v121, 16, v91
	v_sub_f32_e32 v89, v89, v98
	v_fmac_f32_e32 v98, v29, v88
	v_cndmask_b32_e64 v88, v117, 0, s[44:45]
	v_and_b32_e32 v95, 0xffff0000, v95
	v_cndmask_b32_e64 v114, v114, 0, s[44:45]
	v_fmac_f32_e32 v98, v33, v89
	v_cndmask_b32_e64 v89, v121, 0, s[42:43]
	v_sub_f32_e32 v88, v88, v113
	v_and_b32_e32 v99, 0xffff0000, v99
	v_and_b32_e32 v91, 0xffff0000, v91
	v_cndmask_b32_e64 v118, v118, 0, s[42:43]
	v_sub_f32_e32 v114, v114, v101
	v_sub_f32_e32 v89, v89, v113
	v_fmac_f32_e32 v113, v30, v88
	v_cndmask_b32_e64 v88, v95, 0, s[44:45]
	v_sub_f32_e32 v118, v118, v101
	v_fmac_f32_e32 v101, v20, v114
	v_fmac_f32_e32 v113, v34, v89
	v_cndmask_b32_e64 v89, v91, 0, s[42:43]
	v_sub_f32_e32 v88, v88, v99
	v_fmac_f32_e32 v101, v24, v118
	v_sub_f32_e32 v89, v89, v99
	v_fmac_f32_e32 v99, v31, v88
	v_mul_f32_e32 v90, v37, v96
	v_fmac_f32_e32 v111, v26, v92
	v_fmac_f32_e32 v99, v35, v89
	v_mul_f32_e32 v89, v36, v101
	v_mul_f32_e32 v90, v90, v90
	v_fmac_f32_e32 v90, v89, v89
	v_mul_f32_e32 v89, v38, v111
	v_fmac_f32_e32 v90, v89, v89
	v_mul_f32_e32 v89, v39, v97
	v_fmac_f32_e32 v90, v89, v89
	v_mul_f32_e32 v89, v40, v112
	v_fmac_f32_e32 v90, v89, v89
	v_mul_f32_e32 v89, v41, v98
	v_fmac_f32_e32 v90, v89, v89
	v_mul_f32_e32 v89, v42, v113
	v_fmac_f32_e32 v90, v89, v89
	v_mul_f32_e32 v89, v43, v99
	v_fmac_f32_e32 v90, v89, v89
	ds_bpermute_b32 v89, v70, v90
	v_cndmask_b32_e64 v88, v103, 0, s[4:5]
	v_cndmask_b32_e64 v92, v102, 0, s[4:5]
	v_cvt_pk_bf16_f32 v92, v92, v88
	v_ashrrev_i32_e32 v127, 31, v126
	s_waitcnt lgkmcnt(0)
	v_add_f32_e32 v89, v90, v89
	ds_bpermute_b32 v97, v71, v89
	v_cndmask_b32_e64 v93, v109, 0, s[4:5]
	v_cndmask_b32_e64 v94, v108, 0, s[4:5]
	v_cndmask_b32_e64 v91, v105, 0, s[4:5]
	v_cndmask_b32_e64 v95, v104, 0, s[4:5]
	s_waitcnt lgkmcnt(0)
	v_add_f32_e32 v88, v89, v97
	ds_bpermute_b32 v89, v72, v88
	v_cndmask_b32_e64 v96, v107, 0, s[4:5]
	v_cndmask_b32_e64 v90, v106, 0, s[4:5]
	v_cvt_pk_bf16_f32 v91, v95, v91
	v_cvt_pk_bf16_f32 v93, v94, v93
	v_lshlrev_b64 v[94:95], 10, v[126:127]
	v_cvt_pk_bf16_f32 v90, v90, v96
	v_lshl_add_u64 v[94:95], v[56:57], 0, v[94:95]
	global_store_dwordx4 v[94:95], v[90:93], off
	s_and_saveexec_b64 s[42:43], s[6:7]
	s_cbranch_execz .Lp2_bend
	s_waitcnt lgkmcnt(0)
	v_add_f32_e32 v88, v88, v89
	v_add_f32_e32 v88, 0x2b8cbccc, v88
	v_rsq_f32_e32 v90, v88
	v_lshlrev_b64 v[88:89], 5, v[126:127]
	v_lshl_add_u64 v[88:89], v[58:59], 0, v[88:89]
	global_store_dword v[88:89], v90, off
	s_branch .Lp2_bend
.Lp2_bend:
	s_or_b64 exec, exec, s[42:43]
	s_branch .LBB0_196
